# accumulator clearing at the start of every GEMM tile with 64 v_mov_b64 instead of 128 v_mov_b32
# speedup vs baseline: 1.0122x; 1.0052x over previous
; template <class Epi, class Sched, bool ALIGN_EPI = false, bool SP2 = false>
; __device__ __forceinline__ void gemm_phase(PG8_LAS unsigned char* lds, const Gemm g, const Sched& S, const Epi& E) {
;     ...
;         const char* nA = has_next ? (const char*)g.A + (size_t)nxt.pm * tstep : cA; const char* nB = has_next ? (const char*)g.Bt + (size_t)nxt.pn * tstep : cB;
;         for (int t = 0; t < nt; t += 2) {
;             const bool last = (t == nt - 2);
;             const char* a1 = cA + (size_t)(t + 1) * kstep;
;             const char* a2 = last ? nA : cA + (size_t)(t + 2) * kstep; const char* b2 = last ? nB : cB + (size_t)(t + 2) * kstep;
;     ...
; #pragma unroll
;         for (int a = 0; a < 2; ++a)
; #pragma unroll
;             for (int b = 0; b < 2; ++b)
; #pragma unroll
;                 for (int m = 0; m < 4; ++m)
; #pragma unroll
;                     for (int n = 0; n < 2; ++n) acc[a][b][m][n] = (f32x4){0.f, 0.f, 0.f, 0.f};
;         cur = nxt; cA = nA; cB = nB; ++ui;
.LBB0_66:
	s_ashr_i32 s15, s14, 31
	s_lshl_b64 s[18:19], s[14:15], 19
	s_add_u32 s18, s78, s18
	s_addc_u32 s19, s79, s19
	s_and_b64 s[20:21], s[0:1], exec
	s_cselect_b32 s15, s19, s25
	s_cselect_b32 s46, s18, s24
	s_ashr_i32 s13, s12, 31
	s_lshl_b64 s[20:21], s[12:13], 19
	s_add_u32 s20, s16, s20
	s_addc_u32 s21, s17, s21
	s_and_b64 s[28:29], s[0:1], exec
	s_cselect_b32 s13, s21, s27
	s_cselect_b32 s47, s20, s26
	s_add_u32 s24, s24, 0x40080
	s_addc_u32 s25, s25, 0
	s_add_u32 s48, s26, 0x100
	v_mov_b64_e32 v[0:1], 0
	v_mov_b64_e32 v[2:3], 0
	v_mov_b64_e32 v[4:5], 0
	v_mov_b64_e32 v[6:7], 0
	v_mov_b64_e32 v[8:9], 0
	v_mov_b64_e32 v[10:11], 0
	v_mov_b64_e32 v[12:13], 0
	v_mov_b64_e32 v[14:15], 0
	v_mov_b64_e32 v[16:17], 0
	v_mov_b64_e32 v[18:19], 0
	v_mov_b64_e32 v[20:21], 0
	v_mov_b64_e32 v[22:23], 0
	v_mov_b64_e32 v[24:25], 0
	v_mov_b64_e32 v[26:27], 0
	v_mov_b64_e32 v[28:29], 0
	v_mov_b64_e32 v[30:31], 0
	v_mov_b64_e32 v[32:33], 0
	v_mov_b64_e32 v[34:35], 0
	v_mov_b64_e32 v[36:37], 0
	v_mov_b64_e32 v[38:39], 0
	v_mov_b64_e32 v[40:41], 0
	v_mov_b64_e32 v[42:43], 0
	v_mov_b64_e32 v[44:45], 0
	v_mov_b64_e32 v[46:47], 0
	v_mov_b64_e32 v[48:49], 0
	v_mov_b64_e32 v[50:51], 0
	v_mov_b64_e32 v[52:53], 0
	v_mov_b64_e32 v[54:55], 0
	v_mov_b64_e32 v[56:57], 0
	v_mov_b64_e32 v[58:59], 0
	v_mov_b64_e32 v[60:61], 0
	v_mov_b64_e32 v[62:63], 0
	v_mov_b64_e32 v[64:65], 0
	v_mov_b64_e32 v[66:67], 0
	v_mov_b64_e32 v[68:69], 0
	v_mov_b64_e32 v[70:71], 0
	v_mov_b64_e32 v[72:73], 0
	v_mov_b64_e32 v[74:75], 0
	v_mov_b64_e32 v[76:77], 0
	v_mov_b64_e32 v[78:79], 0
	v_mov_b64_e32 v[80:81], 0
	v_mov_b64_e32 v[82:83], 0
	v_mov_b64_e32 v[84:85], 0
	v_mov_b64_e32 v[86:87], 0
	v_mov_b64_e32 v[88:89], 0
	v_mov_b64_e32 v[90:91], 0
	v_mov_b64_e32 v[92:93], 0
	v_mov_b64_e32 v[94:95], 0
	v_mov_b64_e32 v[96:97], 0
	v_mov_b64_e32 v[98:99], 0
	v_mov_b64_e32 v[100:101], 0
	v_mov_b64_e32 v[102:103], 0
	v_mov_b64_e32 v[104:105], 0
	v_mov_b64_e32 v[106:107], 0
	v_mov_b64_e32 v[108:109], 0
	v_mov_b64_e32 v[110:111], 0
	v_mov_b64_e32 v[112:113], 0
	v_mov_b64_e32 v[114:115], 0
	v_mov_b64_e32 v[116:117], 0
	v_mov_b64_e32 v[118:119], 0
	v_mov_b64_e32 v[120:121], 0
	v_mov_b64_e32 v[122:123], 0
	v_mov_b64_e32 v[124:125], 0
	v_mov_b64_e32 v[126:127], 0
	s_addc_u32 s49, s27, 0
	s_mov_b32 s50, -2
	s_waitcnt vmcnt(0)

; template <class Epi, class Sched, bool ALIGN_EPI = false, bool SP2 = false>
; __device__ __forceinline__ void gemm_phase(PG8_LAS unsigned char* lds, const Gemm g, const Sched& S, const Epi& E) {
;     ...
;         const char* nA = has_next ? (const char*)g.A + (size_t)nxt.pm * tstep : cA; const char* nB = has_next ? (const char*)g.Bt + (size_t)nxt.pn * tstep : cB;
;         for (int t = 0; t < nt; t += 2) {
;             const bool last = (t == nt - 2);
;             const char* a1 = cA + (size_t)(t + 1) * kstep;
;             const char* a2 = last ? nA : cA + (size_t)(t + 2) * kstep; const char* b2 = last ? nB : cB + (size_t)(t + 2) * kstep;
;     ...
; #pragma unroll
;         for (int a = 0; a < 2; ++a)
; #pragma unroll
;             for (int b = 0; b < 2; ++b)
; #pragma unroll
;                 for (int m = 0; m < 4; ++m)
; #pragma unroll
;                     for (int n = 0; n < 2; ++n) acc[a][b][m][n] = (f32x4){0.f, 0.f, 0.f, 0.f};
;         cur = nxt; cA = nA; cB = nB; ++ui;
.LBB0_659:
	s_ashr_i32 s29, s28, 31
	s_lshl_b64 s[30:31], s[28:29], 19
	s_add_u32 s30, s10, s30
	s_addc_u32 s31, s11, s31
	s_and_b64 s[34:35], s[4:5], exec
	s_cselect_b32 s29, s31, s39
	s_cselect_b32 s37, s30, s38
	s_ashr_i32 s27, s26, 31
	s_lshl_b64 s[34:35], s[26:27], 19
	s_add_u32 s34, s6, s34
	s_addc_u32 s35, s7, s35
	s_and_b64 s[42:43], s[4:5], exec
	s_cselect_b32 s27, s35, s41
	s_cselect_b32 s57, s34, s40
	s_add_u32 s38, s38, 0x40080
	s_addc_u32 s39, s39, 0
	s_add_u32 s58, s40, 0x100
	v_mov_b64_e32 v[0:1], 0
	v_mov_b64_e32 v[2:3], 0
	v_mov_b64_e32 v[4:5], 0
	v_mov_b64_e32 v[6:7], 0
	v_mov_b64_e32 v[8:9], 0
	v_mov_b64_e32 v[10:11], 0
	v_mov_b64_e32 v[12:13], 0
	v_mov_b64_e32 v[14:15], 0
	v_mov_b64_e32 v[16:17], 0
	v_mov_b64_e32 v[18:19], 0
	v_mov_b64_e32 v[20:21], 0
	v_mov_b64_e32 v[22:23], 0
	v_mov_b64_e32 v[24:25], 0
	v_mov_b64_e32 v[26:27], 0
	v_mov_b64_e32 v[28:29], 0
	v_mov_b64_e32 v[30:31], 0
	v_mov_b64_e32 v[32:33], 0
	v_mov_b64_e32 v[34:35], 0
	v_mov_b64_e32 v[36:37], 0
	v_mov_b64_e32 v[38:39], 0
	v_mov_b64_e32 v[40:41], 0
	v_mov_b64_e32 v[42:43], 0
	v_mov_b64_e32 v[44:45], 0
	v_mov_b64_e32 v[46:47], 0
	v_mov_b64_e32 v[48:49], 0
	v_mov_b64_e32 v[50:51], 0
	v_mov_b64_e32 v[52:53], 0
	v_mov_b64_e32 v[54:55], 0
	v_mov_b64_e32 v[56:57], 0
	v_mov_b64_e32 v[58:59], 0
	v_mov_b64_e32 v[60:61], 0
	v_mov_b64_e32 v[62:63], 0
	v_mov_b64_e32 v[64:65], 0
	v_mov_b64_e32 v[66:67], 0
	v_mov_b64_e32 v[68:69], 0
	v_mov_b64_e32 v[70:71], 0
	v_mov_b64_e32 v[72:73], 0
	v_mov_b64_e32 v[74:75], 0
	v_mov_b64_e32 v[76:77], 0
	v_mov_b64_e32 v[78:79], 0
	v_mov_b64_e32 v[80:81], 0
	v_mov_b64_e32 v[82:83], 0
	v_mov_b64_e32 v[84:85], 0
	v_mov_b64_e32 v[86:87], 0
	v_mov_b64_e32 v[88:89], 0
	v_mov_b64_e32 v[90:91], 0
	v_mov_b64_e32 v[92:93], 0
	v_mov_b64_e32 v[94:95], 0
	v_mov_b64_e32 v[96:97], 0
	v_mov_b64_e32 v[98:99], 0
	v_mov_b64_e32 v[100:101], 0
	v_mov_b64_e32 v[102:103], 0
	v_mov_b64_e32 v[104:105], 0
	v_mov_b64_e32 v[106:107], 0
	v_mov_b64_e32 v[108:109], 0
	v_mov_b64_e32 v[110:111], 0
	v_mov_b64_e32 v[112:113], 0
	v_mov_b64_e32 v[114:115], 0
	v_mov_b64_e32 v[116:117], 0
	v_mov_b64_e32 v[118:119], 0
	v_mov_b64_e32 v[120:121], 0
	v_mov_b64_e32 v[122:123], 0
	v_mov_b64_e32 v[124:125], 0
	v_mov_b64_e32 v[126:127], 0
	s_addc_u32 s59, s41, 0
	s_mov_b32 s60, -2
	s_waitcnt lgkmcnt(0)
	s_waitcnt vmcnt(0)

; template <class Epi, class Sched, bool ALIGN_EPI = false, bool SP2 = false>
; __device__ __forceinline__ void gemm_phase(PG8_LAS unsigned char* lds, const Gemm g, const Sched& S, const Epi& E) {
;     ...
;         const char* nA = has_next ? (const char*)g.A + (size_t)nxt.pm * tstep : cA; const char* nB = has_next ? (const char*)g.Bt + (size_t)nxt.pn * tstep : cB;
;         for (int t = 0; t < nt; t += 2) {
;             const bool last = (t == nt - 2);
;             const char* a1 = cA + (size_t)(t + 1) * kstep;
;             const char* a2 = last ? nA : cA + (size_t)(t + 2) * kstep; const char* b2 = last ? nB : cB + (size_t)(t + 2) * kstep;
;     ...
; #pragma unroll
;         for (int a = 0; a < 2; ++a)
; #pragma unroll
;             for (int b = 0; b < 2; ++b)
; #pragma unroll
;                 for (int m = 0; m < 4; ++m)
; #pragma unroll
;                     for (int n = 0; n < 2; ++n) acc[a][b][m][n] = (f32x4){0.f, 0.f, 0.f, 0.f};
;         cur = nxt; cA = nA; cB = nB; ++ui;
.LBB0_744:
	s_ashr_i32 s43, s42, 31
	s_lshl_b64 s[12:13], s[42:43], 19
	s_add_u32 s44, s2, s12
	s_addc_u32 s45, s3, s13
	s_and_b64 s[12:13], s[4:5], exec
	s_cselect_b32 s43, s45, s9
	s_cselect_b32 s67, s44, s8
	s_ashr_i32 s41, s40, 31
	s_lshl_b64 s[12:13], s[40:41], 19
	s_add_u32 s46, s18, s12
	s_addc_u32 s47, s19, s13
	s_and_b64 s[12:13], s[4:5], exec
	s_cselect_b32 s41, s47, s11
	s_cselect_b32 s68, s46, s10
	s_add_u32 s69, s10, 0x100
	v_mov_b64_e32 v[0:1], 0
	v_mov_b64_e32 v[2:3], 0
	v_mov_b64_e32 v[4:5], 0
	v_mov_b64_e32 v[6:7], 0
	v_mov_b64_e32 v[8:9], 0
	v_mov_b64_e32 v[10:11], 0
	v_mov_b64_e32 v[12:13], 0
	v_mov_b64_e32 v[14:15], 0
	v_mov_b64_e32 v[16:17], 0
	v_mov_b64_e32 v[18:19], 0
	v_mov_b64_e32 v[20:21], 0
	v_mov_b64_e32 v[22:23], 0
	v_mov_b64_e32 v[24:25], 0
	v_mov_b64_e32 v[26:27], 0
	v_mov_b64_e32 v[28:29], 0
	v_mov_b64_e32 v[30:31], 0
	v_mov_b64_e32 v[32:33], 0
	v_mov_b64_e32 v[34:35], 0
	v_mov_b64_e32 v[36:37], 0
	v_mov_b64_e32 v[38:39], 0
	v_mov_b64_e32 v[40:41], 0
	v_mov_b64_e32 v[42:43], 0
	v_mov_b64_e32 v[44:45], 0
	v_mov_b64_e32 v[46:47], 0
	v_mov_b64_e32 v[48:49], 0
	v_mov_b64_e32 v[50:51], 0
	v_mov_b64_e32 v[52:53], 0
	v_mov_b64_e32 v[54:55], 0
	v_mov_b64_e32 v[56:57], 0
	v_mov_b64_e32 v[58:59], 0
	v_mov_b64_e32 v[60:61], 0
	v_mov_b64_e32 v[62:63], 0
	v_mov_b64_e32 v[64:65], 0
	v_mov_b64_e32 v[66:67], 0
	v_mov_b64_e32 v[68:69], 0
	v_mov_b64_e32 v[70:71], 0
	v_mov_b64_e32 v[72:73], 0
	v_mov_b64_e32 v[74:75], 0
	v_mov_b64_e32 v[76:77], 0
	v_mov_b64_e32 v[78:79], 0
	v_mov_b64_e32 v[80:81], 0
	v_mov_b64_e32 v[82:83], 0
	v_mov_b64_e32 v[84:85], 0
	v_mov_b64_e32 v[86:87], 0
	v_mov_b64_e32 v[88:89], 0
	v_mov_b64_e32 v[90:91], 0
	v_mov_b64_e32 v[92:93], 0
	v_mov_b64_e32 v[94:95], 0
	v_mov_b64_e32 v[96:97], 0
	v_mov_b64_e32 v[98:99], 0
	v_mov_b64_e32 v[100:101], 0
	v_mov_b64_e32 v[102:103], 0
	v_mov_b64_e32 v[104:105], 0
	v_mov_b64_e32 v[106:107], 0
	v_mov_b64_e32 v[108:109], 0
	v_mov_b64_e32 v[110:111], 0
	v_mov_b64_e32 v[112:113], 0
	v_mov_b64_e32 v[114:115], 0
	v_mov_b64_e32 v[116:117], 0
	v_mov_b64_e32 v[118:119], 0
	v_mov_b64_e32 v[120:121], 0
	v_mov_b64_e32 v[122:123], 0
	v_mov_b64_e32 v[124:125], 0
	v_mov_b64_e32 v[126:127], 0
	s_addc_u32 s70, s11, 0
	s_mov_b32 s71, -2

; template <class Epi, class Sched, bool ALIGN_EPI = false, bool SP2 = false>
; __device__ __forceinline__ void gemm_phase(PG8_LAS unsigned char* lds, const Gemm g, const Sched& S, const Epi& E) {
;     ...
;         for (int t = 0; t < nt; t += 2) {
;             const bool last = (t == nt - 2);
;             const char* a1 = cA + (size_t)(t + 1) * kstep;
;             const char* a2 = last ? nA : cA + (size_t)(t + 2) * kstep; const char* b2 = last ? nB : cB + (size_t)(t + 2) * kstep;
;     ...
; #pragma unroll
;         for (int a = 0; a < 2; ++a)
; #pragma unroll
;             for (int b = 0; b < 2; ++b)
; #pragma unroll
;                 for (int m = 0; m < 4; ++m)
; #pragma unroll
;                     for (int n = 0; n < 2; ++n) acc[a][b][m][n] = (f32x4){0.f, 0.f, 0.f, 0.f};
;         cur = nxt; cA = nA; cB = nB; ++ui;
.LBB0_912:
	s_add_u32 s28, s28, 0xb0080
	s_addc_u32 s29, s29, 0
	s_add_u32 s52, s30, 0x100
	v_mov_b64_e32 v[0:1], 0
	v_mov_b64_e32 v[2:3], 0
	v_mov_b64_e32 v[4:5], 0
	v_mov_b64_e32 v[6:7], 0
	v_mov_b64_e32 v[8:9], 0
	v_mov_b64_e32 v[10:11], 0
	v_mov_b64_e32 v[12:13], 0
	v_mov_b64_e32 v[14:15], 0
	v_mov_b64_e32 v[16:17], 0
	v_mov_b64_e32 v[18:19], 0
	v_mov_b64_e32 v[20:21], 0
	v_mov_b64_e32 v[22:23], 0
	v_mov_b64_e32 v[24:25], 0
	v_mov_b64_e32 v[26:27], 0
	v_mov_b64_e32 v[28:29], 0
	v_mov_b64_e32 v[30:31], 0
	v_mov_b64_e32 v[32:33], 0
	v_mov_b64_e32 v[34:35], 0
	v_mov_b64_e32 v[36:37], 0
	v_mov_b64_e32 v[38:39], 0
	v_mov_b64_e32 v[40:41], 0
	v_mov_b64_e32 v[42:43], 0
	v_mov_b64_e32 v[44:45], 0
	v_mov_b64_e32 v[46:47], 0
	v_mov_b64_e32 v[48:49], 0
	v_mov_b64_e32 v[50:51], 0
	v_mov_b64_e32 v[52:53], 0
	v_mov_b64_e32 v[54:55], 0
	v_mov_b64_e32 v[56:57], 0
	v_mov_b64_e32 v[58:59], 0
	v_mov_b64_e32 v[60:61], 0
	v_mov_b64_e32 v[62:63], 0
	v_mov_b64_e32 v[64:65], 0
	v_mov_b64_e32 v[66:67], 0
	v_mov_b64_e32 v[68:69], 0
	v_mov_b64_e32 v[70:71], 0
	v_mov_b64_e32 v[72:73], 0
	v_mov_b64_e32 v[74:75], 0
	v_mov_b64_e32 v[76:77], 0
	v_mov_b64_e32 v[78:79], 0
	v_mov_b64_e32 v[80:81], 0
	v_mov_b64_e32 v[82:83], 0
	v_mov_b64_e32 v[84:85], 0
	v_mov_b64_e32 v[86:87], 0
	v_mov_b64_e32 v[88:89], 0
	v_mov_b64_e32 v[90:91], 0
	v_mov_b64_e32 v[92:93], 0
	v_mov_b64_e32 v[94:95], 0
	v_mov_b64_e32 v[96:97], 0
	v_mov_b64_e32 v[98:99], 0
	v_mov_b64_e32 v[100:101], 0
	v_mov_b64_e32 v[102:103], 0
	v_mov_b64_e32 v[104:105], 0
	v_mov_b64_e32 v[106:107], 0
	v_mov_b64_e32 v[108:109], 0
	v_mov_b64_e32 v[110:111], 0
	v_mov_b64_e32 v[112:113], 0
	v_mov_b64_e32 v[114:115], 0
	v_mov_b64_e32 v[116:117], 0
	v_mov_b64_e32 v[118:119], 0
	v_mov_b64_e32 v[120:121], 0
	v_mov_b64_e32 v[122:123], 0
	v_mov_b64_e32 v[124:125], 0
	v_mov_b64_e32 v[126:127], 0
	s_addc_u32 s53, s31, 0
	s_mov_b32 s54, -2
	s_waitcnt lgkmcnt(0)
	s_waitcnt vmcnt(0)
